# v14 + B1 z-tile epilogue rinv loads hoisted + attention segment prologue: lead-in and first block loads issued together
# baseline (speedup 1.0000x reference)
.LBB0_162:
	v_lshl_add_u64 v[134:135], v[152:153], 2, s[16:17]
	global_load_dword v166, v[134:135], off
	global_load_dword v201, v[134:135], off offset:64
	global_load_dword v202, v[134:135], off offset:128
	global_load_dword v203, v[134:135], off offset:192
	global_load_dword v204, v[134:135], off offset:512
	global_load_dword v205, v[134:135], off offset:576
	global_load_dword v206, v[134:135], off offset:640
	global_load_dword v207, v[134:135], off offset:704
	v_lshl_add_u32 v132, s48, 8, v177
	v_mov_b32_e32 v133, v2
	v_lshlrev_b64 v[160:161], 11, v[152:153]
	v_lshl_add_u64 v[162:163], s[14:15], 0, v[160:161]
	v_lshlrev_b64 v[160:161], 1, v[132:133]
	v_lshl_add_u64 v[132:133], v[162:163], 0, v[160:161]
	v_ashrrev_i32_e32 v159, 31, v158
	v_ashrrev_i32_e32 v157, 31, v156
	v_ashrrev_i32_e32 v155, 31, v154
	s_mov_b64 s[0:1], 0x40000
	s_waitcnt vmcnt(0)
	v_pk_mul_f32 v[164:165], v[128:129], v[166:167] op_sel_hi:[1,0]
	s_nop 0
	v_mul_f32_e32 v151, 0xbfb8aa3b, v164
	v_exp_f32_e32 v151, v151
	v_pk_mul_f32 v[162:163], v[130:131], v[166:167] op_sel_hi:[1,0]
	v_pk_mul_f32 v[170:171], v[124:125], v[166:167] op_sel_hi:[1,0]
	v_add_f32_e32 v151, 1.0, v151
	v_rcp_f32_e32 v168, v151
	v_mul_f32_e32 v151, 0xbfb8aa3b, v165
	v_exp_f32_e32 v151, v151
	s_nop 0
	v_add_f32_e32 v151, 1.0, v151
	v_rcp_f32_e32 v169, v151
	v_mul_f32_e32 v151, 0xbfb8aa3b, v162
	v_exp_f32_e32 v151, v151
	v_pk_mul_f32 v[164:165], v[164:165], v[168:169]
	v_add_f32_e32 v151, 1.0, v151
	v_rcp_f32_e32 v168, v151
	v_mul_f32_e32 v151, 0xbfb8aa3b, v163
	v_exp_f32_e32 v151, v151
	s_nop 0
	v_add_f32_e32 v151, 1.0, v151
	v_rcp_f32_e32 v169, v151
	v_mul_f32_e32 v151, 0xbfb8aa3b, v170
	v_exp_f32_e32 v151, v151
	v_pk_mul_f32 v[168:169], v[162:163], v[168:169]
	v_pk_mul_f32 v[162:163], v[126:127], v[166:167] op_sel_hi:[1,0]
	v_add_f32_e32 v151, 1.0, v151
	v_rcp_f32_e32 v172, v151
	v_mul_f32_e32 v151, 0xbfb8aa3b, v171
	v_exp_f32_e32 v151, v151
	s_nop 0
	v_add_f32_e32 v151, 1.0, v151
	v_rcp_f32_e32 v173, v151
	v_mul_f32_e32 v151, 0xbfb8aa3b, v162
	v_exp_f32_e32 v151, v151
	v_pk_mul_f32 v[170:171], v[170:171], v[172:173]
	v_add_f32_e32 v151, 1.0, v151
	v_rcp_f32_e32 v172, v151
	v_mul_f32_e32 v151, 0xbfb8aa3b, v163
	v_exp_f32_e32 v151, v151
	s_nop 0
	v_add_f32_e32 v151, 1.0, v151
	v_rcp_f32_e32 v173, v151
	s_nop 0
	v_pk_mul_f32 v[172:173], v[162:163], v[172:173]
	v_cvt_pk_bf16_f32 v162, v164, v165
	v_cvt_pk_bf16_f32 v163, v168, v169
	v_cvt_pk_bf16_f32 v164, v170, v171
	v_cvt_pk_bf16_f32 v165, v172, v173
	global_store_dwordx4 v[132:133], v[162:165], off
	s_nop 1
	v_pk_mul_f32 v[162:163], v[120:121], v[166:167] op_sel_hi:[1,0]
	v_pk_mul_f32 v[164:165], v[122:123], v[166:167] op_sel_hi:[1,0]
	v_mul_f32_e32 v151, 0xbfb8aa3b, v162
	v_exp_f32_e32 v151, v151
	s_nop 0
	v_add_f32_e32 v151, 1.0, v151
	v_rcp_f32_e32 v168, v151
	v_mul_f32_e32 v151, 0xbfb8aa3b, v163
	v_exp_f32_e32 v151, v151
	s_nop 0
	v_add_f32_e32 v151, 1.0, v151
	v_rcp_f32_e32 v169, v151
	v_mul_f32_e32 v151, 0xbfb8aa3b, v164
	v_exp_f32_e32 v151, v151
	v_pk_mul_f32 v[162:163], v[162:163], v[168:169]
	s_nop 0
	v_cvt_pk_bf16_f32 v162, v162, v163
	v_add_f32_e32 v151, 1.0, v151
	v_rcp_f32_e32 v168, v151
	v_mul_f32_e32 v151, 0xbfb8aa3b, v165
	v_exp_f32_e32 v151, v151
	s_nop 0
	v_add_f32_e32 v151, 1.0, v151
	v_rcp_f32_e32 v169, v151
	s_nop 0
	v_pk_mul_f32 v[164:165], v[164:165], v[168:169]
	v_pk_mul_f32 v[168:169], v[118:119], v[166:167] op_sel_hi:[1,0]
	v_pk_mul_f32 v[166:167], v[116:117], v[166:167] op_sel_hi:[1,0]
	v_cvt_pk_bf16_f32 v163, v164, v165
	v_mul_f32_e32 v151, 0xbfb8aa3b, v166
	v_exp_f32_e32 v151, v151
	s_nop 0
	v_add_f32_e32 v151, 1.0, v151
	v_rcp_f32_e32 v170, v151
	v_mul_f32_e32 v151, 0xbfb8aa3b, v167
	v_exp_f32_e32 v151, v151
	s_nop 0
	v_add_f32_e32 v151, 1.0, v151
	v_rcp_f32_e32 v171, v151
	v_mul_f32_e32 v151, 0xbfb8aa3b, v168
	v_exp_f32_e32 v151, v151
	v_pk_mul_f32 v[166:167], v[166:167], v[170:171]
	s_nop 0
	v_cvt_pk_bf16_f32 v164, v166, v167
	v_add_f32_e32 v151, 1.0, v151
	v_rcp_f32_e32 v170, v151
	v_mul_f32_e32 v151, 0xbfb8aa3b, v169
	v_exp_f32_e32 v151, v151
	s_nop 0
	v_add_f32_e32 v151, 1.0, v151
	v_rcp_f32_e32 v171, v151
	s_nop 0
	v_pk_mul_f32 v[168:169], v[168:169], v[170:171]
	s_nop 0
	v_cvt_pk_bf16_f32 v165, v168, v169
	global_store_dwordx4 v[132:133], v[162:165], off offset:256
	s_nop 1
	v_mov_b32_e32 v168, v201
	v_pk_mul_f32 v[166:167], v[112:113], v[168:169] op_sel_hi:[1,0]
	s_nop 0
	v_mul_f32_e32 v151, 0xbfb8aa3b, v166
	v_exp_f32_e32 v151, v151
	v_pk_mul_f32 v[164:165], v[114:115], v[168:169] op_sel_hi:[1,0]
	v_pk_mul_f32 v[172:173], v[108:109], v[168:169] op_sel_hi:[1,0]
	v_lshlrev_b64 v[162:163], 11, v[158:159]
	v_add_f32_e32 v151, 1.0, v151
	v_rcp_f32_e32 v170, v151
	v_mul_f32_e32 v151, 0xbfb8aa3b, v167
	v_exp_f32_e32 v151, v151
	v_lshl_add_u64 v[162:163], s[14:15], 0, v[162:163]
	v_lshl_add_u64 v[162:163], v[162:163], 0, v[160:161]
	v_add_f32_e32 v151, 1.0, v151
	v_rcp_f32_e32 v171, v151
	v_mul_f32_e32 v151, 0xbfb8aa3b, v164
	v_exp_f32_e32 v151, v151
	v_pk_mul_f32 v[166:167], v[166:167], v[170:171]
	v_add_f32_e32 v151, 1.0, v151
	v_rcp_f32_e32 v170, v151
	v_mul_f32_e32 v151, 0xbfb8aa3b, v165
	v_exp_f32_e32 v151, v151
	s_nop 0
	v_add_f32_e32 v151, 1.0, v151
	v_rcp_f32_e32 v171, v151
	v_mul_f32_e32 v151, 0xbfb8aa3b, v172
	v_exp_f32_e32 v151, v151
	v_pk_mul_f32 v[170:171], v[164:165], v[170:171]
	v_pk_mul_f32 v[164:165], v[110:111], v[168:169] op_sel_hi:[1,0]
	v_add_f32_e32 v151, 1.0, v151
	v_rcp_f32_e32 v174, v151
	v_mul_f32_e32 v151, 0xbfb8aa3b, v173
	v_exp_f32_e32 v151, v151
	s_nop 0
	v_add_f32_e32 v151, 1.0, v151
	v_rcp_f32_e32 v175, v151
	v_mul_f32_e32 v151, 0xbfb8aa3b, v164
	v_exp_f32_e32 v151, v151
	v_pk_mul_f32 v[172:173], v[172:173], v[174:175]
	v_add_f32_e32 v151, 1.0, v151
	v_rcp_f32_e32 v174, v151
	v_mul_f32_e32 v151, 0xbfb8aa3b, v165
	v_exp_f32_e32 v151, v151
	s_nop 0
	v_add_f32_e32 v151, 1.0, v151
	v_rcp_f32_e32 v175, v151
	s_nop 0
	v_pk_mul_f32 v[174:175], v[164:165], v[174:175]
	v_cvt_pk_bf16_f32 v164, v166, v167
	v_cvt_pk_bf16_f32 v165, v170, v171
	v_cvt_pk_bf16_f32 v166, v172, v173
	v_cvt_pk_bf16_f32 v167, v174, v175
	global_store_dwordx4 v[162:163], v[164:167], off
	s_nop 1
	v_pk_mul_f32 v[164:165], v[104:105], v[168:169] op_sel_hi:[1,0]
	v_pk_mul_f32 v[166:167], v[106:107], v[168:169] op_sel_hi:[1,0]
	v_mul_f32_e32 v151, 0xbfb8aa3b, v164
	v_exp_f32_e32 v151, v151
	s_nop 0
	v_add_f32_e32 v151, 1.0, v151
	v_rcp_f32_e32 v170, v151
	v_mul_f32_e32 v151, 0xbfb8aa3b, v165
	v_exp_f32_e32 v151, v151
	s_nop 0
	v_add_f32_e32 v151, 1.0, v151
	v_rcp_f32_e32 v171, v151
	v_mul_f32_e32 v151, 0xbfb8aa3b, v166
	v_exp_f32_e32 v151, v151
	v_pk_mul_f32 v[164:165], v[164:165], v[170:171]
	s_nop 0
	v_cvt_pk_bf16_f32 v164, v164, v165
	v_add_f32_e32 v151, 1.0, v151
	v_rcp_f32_e32 v170, v151
	v_mul_f32_e32 v151, 0xbfb8aa3b, v167
	v_exp_f32_e32 v151, v151
	s_nop 0
	v_add_f32_e32 v151, 1.0, v151
	v_rcp_f32_e32 v171, v151
	s_nop 0
	v_pk_mul_f32 v[166:167], v[166:167], v[170:171]
	v_pk_mul_f32 v[170:171], v[102:103], v[168:169] op_sel_hi:[1,0]
	v_pk_mul_f32 v[168:169], v[100:101], v[168:169] op_sel_hi:[1,0]
	v_cvt_pk_bf16_f32 v165, v166, v167
	v_mul_f32_e32 v151, 0xbfb8aa3b, v168
	v_exp_f32_e32 v151, v151
	s_nop 0
	v_add_f32_e32 v151, 1.0, v151
	v_rcp_f32_e32 v172, v151
	v_mul_f32_e32 v151, 0xbfb8aa3b, v169
	v_exp_f32_e32 v151, v151
	s_nop 0
	v_add_f32_e32 v151, 1.0, v151
	v_rcp_f32_e32 v173, v151
	v_mul_f32_e32 v151, 0xbfb8aa3b, v170
	v_exp_f32_e32 v151, v151
	v_pk_mul_f32 v[168:169], v[168:169], v[172:173]
	s_nop 0
	v_cvt_pk_bf16_f32 v166, v168, v169
	v_add_f32_e32 v151, 1.0, v151
	v_rcp_f32_e32 v172, v151
	v_mul_f32_e32 v151, 0xbfb8aa3b, v171
	v_exp_f32_e32 v151, v151
	s_nop 0
	v_add_f32_e32 v151, 1.0, v151
	v_rcp_f32_e32 v173, v151
	s_nop 0
	v_pk_mul_f32 v[170:171], v[170:171], v[172:173]
	s_nop 0
	v_cvt_pk_bf16_f32 v167, v170, v171
	global_store_dwordx4 v[162:163], v[164:167], off offset:256
	s_nop 1
	v_mov_b32_e32 v168, v202
	v_lshlrev_b64 v[162:163], 11, v[156:157]
	v_lshl_add_u64 v[162:163], s[14:15], 0, v[162:163]
	v_lshl_add_u64 v[162:163], v[162:163], 0, v[160:161]
	v_pk_mul_f32 v[166:167], v[96:97], v[168:169] op_sel_hi:[1,0]
	s_nop 0
	v_mul_f32_e32 v151, 0xbfb8aa3b, v166
	v_exp_f32_e32 v151, v151
	v_pk_mul_f32 v[164:165], v[98:99], v[168:169] op_sel_hi:[1,0]
	v_pk_mul_f32 v[172:173], v[92:93], v[168:169] op_sel_hi:[1,0]
	v_add_f32_e32 v151, 1.0, v151
	v_rcp_f32_e32 v170, v151
	v_mul_f32_e32 v151, 0xbfb8aa3b, v167
	v_exp_f32_e32 v151, v151
	s_nop 0
	v_add_f32_e32 v151, 1.0, v151
	v_rcp_f32_e32 v171, v151
	v_mul_f32_e32 v151, 0xbfb8aa3b, v164
	v_exp_f32_e32 v151, v151
	v_pk_mul_f32 v[166:167], v[166:167], v[170:171]
	v_add_f32_e32 v151, 1.0, v151
	v_rcp_f32_e32 v170, v151
	v_mul_f32_e32 v151, 0xbfb8aa3b, v165
	v_exp_f32_e32 v151, v151
	s_nop 0
	v_add_f32_e32 v151, 1.0, v151
	v_rcp_f32_e32 v171, v151
	v_mul_f32_e32 v151, 0xbfb8aa3b, v172
	v_exp_f32_e32 v151, v151
	v_pk_mul_f32 v[170:171], v[164:165], v[170:171]
	v_pk_mul_f32 v[164:165], v[94:95], v[168:169] op_sel_hi:[1,0]
	v_add_f32_e32 v151, 1.0, v151
	v_rcp_f32_e32 v174, v151
	v_mul_f32_e32 v151, 0xbfb8aa3b, v173
	v_exp_f32_e32 v151, v151
	s_nop 0
	v_add_f32_e32 v151, 1.0, v151
	v_rcp_f32_e32 v175, v151
	v_mul_f32_e32 v151, 0xbfb8aa3b, v164
	v_exp_f32_e32 v151, v151
	v_pk_mul_f32 v[172:173], v[172:173], v[174:175]
	v_add_f32_e32 v151, 1.0, v151
	v_rcp_f32_e32 v174, v151
	v_mul_f32_e32 v151, 0xbfb8aa3b, v165
	v_exp_f32_e32 v151, v151
	s_nop 0
	v_add_f32_e32 v151, 1.0, v151
	v_rcp_f32_e32 v175, v151
	s_nop 0
	v_pk_mul_f32 v[174:175], v[164:165], v[174:175]
	v_cvt_pk_bf16_f32 v164, v166, v167
	v_cvt_pk_bf16_f32 v165, v170, v171
	v_cvt_pk_bf16_f32 v166, v172, v173
	v_cvt_pk_bf16_f32 v167, v174, v175
	global_store_dwordx4 v[162:163], v[164:167], off
	s_nop 1
	v_pk_mul_f32 v[164:165], v[88:89], v[168:169] op_sel_hi:[1,0]
	v_pk_mul_f32 v[166:167], v[90:91], v[168:169] op_sel_hi:[1,0]
	v_mul_f32_e32 v151, 0xbfb8aa3b, v164
	v_exp_f32_e32 v151, v151
	s_nop 0
	v_add_f32_e32 v151, 1.0, v151
	v_rcp_f32_e32 v170, v151
	v_mul_f32_e32 v151, 0xbfb8aa3b, v165
	v_exp_f32_e32 v151, v151
	s_nop 0
	v_add_f32_e32 v151, 1.0, v151
	v_rcp_f32_e32 v171, v151
	v_mul_f32_e32 v151, 0xbfb8aa3b, v166
	v_exp_f32_e32 v151, v151
	v_pk_mul_f32 v[164:165], v[164:165], v[170:171]
	s_nop 0
	v_cvt_pk_bf16_f32 v164, v164, v165
	v_add_f32_e32 v151, 1.0, v151
	v_rcp_f32_e32 v170, v151
	v_mul_f32_e32 v151, 0xbfb8aa3b, v167
	v_exp_f32_e32 v151, v151
	s_nop 0
	v_add_f32_e32 v151, 1.0, v151
	v_rcp_f32_e32 v171, v151
	s_nop 0
	v_pk_mul_f32 v[166:167], v[166:167], v[170:171]
	v_pk_mul_f32 v[170:171], v[86:87], v[168:169] op_sel_hi:[1,0]
	v_pk_mul_f32 v[168:169], v[84:85], v[168:169] op_sel_hi:[1,0]
	v_cvt_pk_bf16_f32 v165, v166, v167
	v_mul_f32_e32 v151, 0xbfb8aa3b, v168
	v_exp_f32_e32 v151, v151
	s_nop 0
	v_add_f32_e32 v151, 1.0, v151
	v_rcp_f32_e32 v172, v151
	v_mul_f32_e32 v151, 0xbfb8aa3b, v169
	v_exp_f32_e32 v151, v151
	s_nop 0
	v_add_f32_e32 v151, 1.0, v151
	v_rcp_f32_e32 v173, v151
	v_mul_f32_e32 v151, 0xbfb8aa3b, v170
	v_exp_f32_e32 v151, v151
	v_pk_mul_f32 v[168:169], v[168:169], v[172:173]
	s_nop 0
	v_cvt_pk_bf16_f32 v166, v168, v169
	v_add_f32_e32 v151, 1.0, v151
	v_rcp_f32_e32 v172, v151
	v_mul_f32_e32 v151, 0xbfb8aa3b, v171
	v_exp_f32_e32 v151, v151
	s_nop 0
	v_add_f32_e32 v151, 1.0, v151
	v_rcp_f32_e32 v173, v151
	s_nop 0
	v_pk_mul_f32 v[170:171], v[170:171], v[172:173]
	s_nop 0
	v_cvt_pk_bf16_f32 v167, v170, v171
	global_store_dwordx4 v[162:163], v[164:167], off offset:256
	s_nop 1
	v_mov_b32_e32 v168, v203
	v_lshlrev_b64 v[162:163], 11, v[154:155]
	v_lshl_add_u64 v[162:163], s[14:15], 0, v[162:163]
	v_lshl_add_u64 v[160:161], v[162:163], 0, v[160:161]
	v_pk_mul_f32 v[164:165], v[80:81], v[168:169] op_sel_hi:[1,0]
	s_nop 0
	v_mul_f32_e32 v151, 0xbfb8aa3b, v164
	v_exp_f32_e32 v151, v151
	v_pk_mul_f32 v[162:163], v[82:83], v[168:169] op_sel_hi:[1,0]
	v_pk_mul_f32 v[170:171], v[76:77], v[168:169] op_sel_hi:[1,0]
	v_add_f32_e32 v151, 1.0, v151
	v_rcp_f32_e32 v166, v151
	v_mul_f32_e32 v151, 0xbfb8aa3b, v165
	v_exp_f32_e32 v151, v151
	s_nop 0
	v_add_f32_e32 v151, 1.0, v151
	v_rcp_f32_e32 v167, v151
	v_mul_f32_e32 v151, 0xbfb8aa3b, v162
	v_exp_f32_e32 v151, v151
	v_pk_mul_f32 v[164:165], v[164:165], v[166:167]
	v_add_f32_e32 v151, 1.0, v151
	v_rcp_f32_e32 v166, v151
	v_mul_f32_e32 v151, 0xbfb8aa3b, v163
	v_exp_f32_e32 v151, v151
	s_nop 0
	v_add_f32_e32 v151, 1.0, v151
	v_rcp_f32_e32 v167, v151
	v_mul_f32_e32 v151, 0xbfb8aa3b, v170
	v_exp_f32_e32 v151, v151
	v_pk_mul_f32 v[166:167], v[162:163], v[166:167]
	v_pk_mul_f32 v[162:163], v[78:79], v[168:169] op_sel_hi:[1,0]
	v_add_f32_e32 v151, 1.0, v151
	v_rcp_f32_e32 v172, v151
	v_mul_f32_e32 v151, 0xbfb8aa3b, v171
	v_exp_f32_e32 v151, v151
	s_nop 0
	v_add_f32_e32 v151, 1.0, v151
	v_rcp_f32_e32 v173, v151
	v_mul_f32_e32 v151, 0xbfb8aa3b, v162
	v_exp_f32_e32 v151, v151
	v_pk_mul_f32 v[170:171], v[170:171], v[172:173]
	v_add_f32_e32 v151, 1.0, v151
	v_rcp_f32_e32 v172, v151
	v_mul_f32_e32 v151, 0xbfb8aa3b, v163
	v_exp_f32_e32 v151, v151
	s_nop 0
	v_add_f32_e32 v151, 1.0, v151
	v_rcp_f32_e32 v173, v151
	s_nop 0
	v_pk_mul_f32 v[172:173], v[162:163], v[172:173]
	v_cvt_pk_bf16_f32 v162, v164, v165
	v_cvt_pk_bf16_f32 v163, v166, v167
	v_cvt_pk_bf16_f32 v164, v170, v171
	v_cvt_pk_bf16_f32 v165, v172, v173
	global_store_dwordx4 v[160:161], v[162:165], off
	s_nop 1
	v_pk_mul_f32 v[162:163], v[72:73], v[168:169] op_sel_hi:[1,0]
	v_pk_mul_f32 v[164:165], v[74:75], v[168:169] op_sel_hi:[1,0]
	v_mul_f32_e32 v151, 0xbfb8aa3b, v162
	v_exp_f32_e32 v151, v151
	s_nop 0
	v_add_f32_e32 v151, 1.0, v151
	v_rcp_f32_e32 v166, v151
	v_mul_f32_e32 v151, 0xbfb8aa3b, v163
	v_exp_f32_e32 v151, v151
	s_nop 0
	v_add_f32_e32 v151, 1.0, v151
	v_rcp_f32_e32 v167, v151
	v_mul_f32_e32 v151, 0xbfb8aa3b, v164
	v_exp_f32_e32 v151, v151
	v_pk_mul_f32 v[162:163], v[162:163], v[166:167]
	s_nop 0
	v_cvt_pk_bf16_f32 v162, v162, v163
	v_add_f32_e32 v151, 1.0, v151
	v_rcp_f32_e32 v166, v151
	v_mul_f32_e32 v151, 0xbfb8aa3b, v165
	v_exp_f32_e32 v151, v151
	s_nop 0
	v_add_f32_e32 v151, 1.0, v151
	v_rcp_f32_e32 v167, v151
	s_nop 0
	v_pk_mul_f32 v[164:165], v[164:165], v[166:167]
	v_pk_mul_f32 v[166:167], v[70:71], v[168:169] op_sel_hi:[1,0]
	v_pk_mul_f32 v[168:169], v[68:69], v[168:169] op_sel_hi:[1,0]
	v_cvt_pk_bf16_f32 v163, v164, v165
	v_mul_f32_e32 v151, 0xbfb8aa3b, v168
	v_exp_f32_e32 v151, v151
	s_nop 0
	v_add_f32_e32 v151, 1.0, v151
	v_rcp_f32_e32 v170, v151
	v_mul_f32_e32 v151, 0xbfb8aa3b, v169
	v_exp_f32_e32 v151, v151
	s_nop 0
	v_add_f32_e32 v151, 1.0, v151
	v_rcp_f32_e32 v171, v151
	v_mul_f32_e32 v151, 0xbfb8aa3b, v166
	v_exp_f32_e32 v151, v151
	v_pk_mul_f32 v[168:169], v[168:169], v[170:171]
	s_nop 0
	v_cvt_pk_bf16_f32 v164, v168, v169
	v_add_f32_e32 v151, 1.0, v151
	v_rcp_f32_e32 v170, v151
	v_mul_f32_e32 v151, 0xbfb8aa3b, v167
	v_exp_f32_e32 v151, v151
	s_nop 0
	v_add_f32_e32 v151, 1.0, v151
	v_rcp_f32_e32 v171, v151
	s_nop 0
	v_pk_mul_f32 v[166:167], v[166:167], v[170:171]
	s_nop 0
	v_cvt_pk_bf16_f32 v165, v166, v167
	global_store_dwordx4 v[160:161], v[162:165], off offset:256
	s_nop 1
	v_mov_b32_e32 v166, v204
	v_lshl_add_u64 v[160:161], v[132:133], 0, s[0:1]
	s_mov_b32 s0, 0x40000
	v_pk_mul_f32 v[164:165], v[64:65], v[166:167] op_sel_hi:[1,0]
	s_nop 0
	v_mul_f32_e32 v151, 0xbfb8aa3b, v164
	v_exp_f32_e32 v151, v151
	v_pk_mul_f32 v[162:163], v[66:67], v[166:167] op_sel_hi:[1,0]
	v_pk_mul_f32 v[170:171], v[60:61], v[166:167] op_sel_hi:[1,0]
	v_add_f32_e32 v151, 1.0, v151
	v_rcp_f32_e32 v168, v151
	v_mul_f32_e32 v151, 0xbfb8aa3b, v165
	v_exp_f32_e32 v151, v151
	s_nop 0
	v_add_f32_e32 v151, 1.0, v151
	v_rcp_f32_e32 v169, v151
	v_mul_f32_e32 v151, 0xbfb8aa3b, v162
	v_exp_f32_e32 v151, v151
	v_pk_mul_f32 v[164:165], v[164:165], v[168:169]
	v_add_f32_e32 v151, 1.0, v151
	v_rcp_f32_e32 v168, v151
	v_mul_f32_e32 v151, 0xbfb8aa3b, v163
	v_exp_f32_e32 v151, v151
	s_nop 0
	v_add_f32_e32 v151, 1.0, v151
	v_rcp_f32_e32 v169, v151
	v_mul_f32_e32 v151, 0xbfb8aa3b, v170
	v_exp_f32_e32 v151, v151
	v_pk_mul_f32 v[168:169], v[162:163], v[168:169]
	v_pk_mul_f32 v[162:163], v[62:63], v[166:167] op_sel_hi:[1,0]
	v_add_f32_e32 v151, 1.0, v151
	v_rcp_f32_e32 v172, v151
	v_mul_f32_e32 v151, 0xbfb8aa3b, v171
	v_exp_f32_e32 v151, v151
	s_nop 0
	v_add_f32_e32 v151, 1.0, v151
	v_rcp_f32_e32 v173, v151
	v_mul_f32_e32 v151, 0xbfb8aa3b, v162
	v_exp_f32_e32 v151, v151
	v_pk_mul_f32 v[170:171], v[170:171], v[172:173]
	v_add_f32_e32 v151, 1.0, v151
	v_rcp_f32_e32 v172, v151
	v_mul_f32_e32 v151, 0xbfb8aa3b, v163
	v_exp_f32_e32 v151, v151
	s_nop 0
	v_add_f32_e32 v151, 1.0, v151
	v_rcp_f32_e32 v173, v151
	s_nop 0
	v_pk_mul_f32 v[172:173], v[162:163], v[172:173]
	v_cvt_pk_bf16_f32 v163, v168, v169
	v_add_co_u32_e32 v168, vcc, s0, v132
	v_cvt_pk_bf16_f32 v162, v164, v165
	v_cvt_pk_bf16_f32 v164, v170, v171
	v_cvt_pk_bf16_f32 v165, v172, v173
	v_addc_co_u32_e32 v169, vcc, 0, v133, vcc
	global_store_dwordx4 v[168:169], v[162:165], off
	s_mov_b64 s[0:1], 0x48000
	s_nop 0
	v_pk_mul_f32 v[162:163], v[56:57], v[166:167] op_sel_hi:[1,0]
	v_pk_mul_f32 v[164:165], v[58:59], v[166:167] op_sel_hi:[1,0]
	v_mul_f32_e32 v151, 0xbfb8aa3b, v162
	v_exp_f32_e32 v151, v151
	s_nop 0
	v_add_f32_e32 v151, 1.0, v151
	v_rcp_f32_e32 v168, v151
	v_mul_f32_e32 v151, 0xbfb8aa3b, v163
	v_exp_f32_e32 v151, v151
	s_nop 0
	v_add_f32_e32 v151, 1.0, v151
	v_rcp_f32_e32 v169, v151
	v_mul_f32_e32 v151, 0xbfb8aa3b, v164
	v_exp_f32_e32 v151, v151
	v_pk_mul_f32 v[162:163], v[162:163], v[168:169]
	s_nop 0
	v_cvt_pk_bf16_f32 v162, v162, v163
	v_add_f32_e32 v151, 1.0, v151
	v_rcp_f32_e32 v168, v151
	v_mul_f32_e32 v151, 0xbfb8aa3b, v165
	v_exp_f32_e32 v151, v151
	s_nop 0
	v_add_f32_e32 v151, 1.0, v151
	v_rcp_f32_e32 v169, v151
	s_nop 0
	v_pk_mul_f32 v[164:165], v[164:165], v[168:169]
	v_pk_mul_f32 v[168:169], v[54:55], v[166:167] op_sel_hi:[1,0]
	v_pk_mul_f32 v[166:167], v[52:53], v[166:167] op_sel_hi:[1,0]
	v_cvt_pk_bf16_f32 v163, v164, v165
	v_mul_f32_e32 v151, 0xbfb8aa3b, v166
	v_exp_f32_e32 v151, v151
	s_nop 0
	v_add_f32_e32 v151, 1.0, v151
	v_rcp_f32_e32 v170, v151
	v_mul_f32_e32 v151, 0xbfb8aa3b, v167
	v_exp_f32_e32 v151, v151
	s_nop 0
	v_add_f32_e32 v151, 1.0, v151
	v_rcp_f32_e32 v171, v151
	v_mul_f32_e32 v151, 0xbfb8aa3b, v168
	v_exp_f32_e32 v151, v151
	v_pk_mul_f32 v[166:167], v[166:167], v[170:171]
	s_nop 0
	v_cvt_pk_bf16_f32 v164, v166, v167
	v_add_f32_e32 v151, 1.0, v151
	v_rcp_f32_e32 v170, v151
	v_mul_f32_e32 v151, 0xbfb8aa3b, v169
	v_exp_f32_e32 v151, v151
	s_nop 0
	v_add_f32_e32 v151, 1.0, v151
	v_rcp_f32_e32 v171, v151
	s_nop 0
	v_pk_mul_f32 v[168:169], v[168:169], v[170:171]
	s_nop 0
	v_cvt_pk_bf16_f32 v165, v168, v169
	global_store_dwordx4 v[160:161], v[162:165], off offset:256
	s_nop 1
	v_mov_b32_e32 v166, v205
	v_lshl_add_u64 v[160:161], v[132:133], 0, s[0:1]
	s_mov_b32 s0, 0x48000
	v_pk_mul_f32 v[164:165], v[48:49], v[166:167] op_sel_hi:[1,0]
	s_nop 0
	v_mul_f32_e32 v151, 0xbfb8aa3b, v164
	v_exp_f32_e32 v151, v151
	v_pk_mul_f32 v[162:163], v[50:51], v[166:167] op_sel_hi:[1,0]
	v_pk_mul_f32 v[170:171], v[44:45], v[166:167] op_sel_hi:[1,0]
	v_add_f32_e32 v151, 1.0, v151
	v_rcp_f32_e32 v168, v151
	v_mul_f32_e32 v151, 0xbfb8aa3b, v165
	v_exp_f32_e32 v151, v151
	s_nop 0
	v_add_f32_e32 v151, 1.0, v151
	v_rcp_f32_e32 v169, v151
	v_mul_f32_e32 v151, 0xbfb8aa3b, v162
	v_exp_f32_e32 v151, v151
	v_pk_mul_f32 v[164:165], v[164:165], v[168:169]
	v_add_f32_e32 v151, 1.0, v151
	v_rcp_f32_e32 v168, v151
	v_mul_f32_e32 v151, 0xbfb8aa3b, v163
	v_exp_f32_e32 v151, v151
	s_nop 0
	v_add_f32_e32 v151, 1.0, v151
	v_rcp_f32_e32 v169, v151
	v_mul_f32_e32 v151, 0xbfb8aa3b, v170
	v_exp_f32_e32 v151, v151
	v_pk_mul_f32 v[168:169], v[162:163], v[168:169]
	v_pk_mul_f32 v[162:163], v[46:47], v[166:167] op_sel_hi:[1,0]
	v_add_f32_e32 v151, 1.0, v151
	v_rcp_f32_e32 v172, v151
	v_mul_f32_e32 v151, 0xbfb8aa3b, v171
	v_exp_f32_e32 v151, v151
	s_nop 0
	v_add_f32_e32 v151, 1.0, v151
	v_rcp_f32_e32 v173, v151
	v_mul_f32_e32 v151, 0xbfb8aa3b, v162
	v_exp_f32_e32 v151, v151
	v_pk_mul_f32 v[170:171], v[170:171], v[172:173]
	v_add_f32_e32 v151, 1.0, v151
	v_rcp_f32_e32 v172, v151
	v_mul_f32_e32 v151, 0xbfb8aa3b, v163
	v_exp_f32_e32 v151, v151
	s_nop 0
	v_add_f32_e32 v151, 1.0, v151
	v_rcp_f32_e32 v173, v151
	s_nop 0
	v_pk_mul_f32 v[172:173], v[162:163], v[172:173]
	v_cvt_pk_bf16_f32 v163, v168, v169
	v_add_co_u32_e32 v168, vcc, s0, v132
	v_cvt_pk_bf16_f32 v162, v164, v165
	v_cvt_pk_bf16_f32 v164, v170, v171
	v_cvt_pk_bf16_f32 v165, v172, v173
	v_addc_co_u32_e32 v169, vcc, 0, v133, vcc
	global_store_dwordx4 v[168:169], v[162:165], off
	s_mov_b64 s[0:1], 0x50000
	s_nop 0
	v_pk_mul_f32 v[162:163], v[40:41], v[166:167] op_sel_hi:[1,0]
	v_pk_mul_f32 v[164:165], v[42:43], v[166:167] op_sel_hi:[1,0]
	v_mul_f32_e32 v151, 0xbfb8aa3b, v162
	v_exp_f32_e32 v151, v151
	s_nop 0
	v_add_f32_e32 v151, 1.0, v151
	v_rcp_f32_e32 v168, v151
	v_mul_f32_e32 v151, 0xbfb8aa3b, v163
	v_exp_f32_e32 v151, v151
	s_nop 0
	v_add_f32_e32 v151, 1.0, v151
	v_rcp_f32_e32 v169, v151
	v_mul_f32_e32 v151, 0xbfb8aa3b, v164
	v_exp_f32_e32 v151, v151
	v_pk_mul_f32 v[162:163], v[162:163], v[168:169]
	s_nop 0
	v_cvt_pk_bf16_f32 v162, v162, v163
	v_add_f32_e32 v151, 1.0, v151
	v_rcp_f32_e32 v168, v151
	v_mul_f32_e32 v151, 0xbfb8aa3b, v165
	v_exp_f32_e32 v151, v151
	s_nop 0
	v_add_f32_e32 v151, 1.0, v151
	v_rcp_f32_e32 v169, v151
	s_nop 0
	v_pk_mul_f32 v[164:165], v[164:165], v[168:169]
	v_pk_mul_f32 v[168:169], v[38:39], v[166:167] op_sel_hi:[1,0]
	v_pk_mul_f32 v[166:167], v[36:37], v[166:167] op_sel_hi:[1,0]
	v_cvt_pk_bf16_f32 v163, v164, v165
	v_mul_f32_e32 v151, 0xbfb8aa3b, v166
	v_exp_f32_e32 v151, v151
	s_nop 0
	v_add_f32_e32 v151, 1.0, v151
	v_rcp_f32_e32 v170, v151
	v_mul_f32_e32 v151, 0xbfb8aa3b, v167
	v_exp_f32_e32 v151, v151
	s_nop 0
	v_add_f32_e32 v151, 1.0, v151
	v_rcp_f32_e32 v171, v151
	v_mul_f32_e32 v151, 0xbfb8aa3b, v168
	v_exp_f32_e32 v151, v151
	v_pk_mul_f32 v[166:167], v[166:167], v[170:171]
	s_nop 0
	v_cvt_pk_bf16_f32 v164, v166, v167
	v_add_f32_e32 v151, 1.0, v151
	v_rcp_f32_e32 v170, v151
	v_mul_f32_e32 v151, 0xbfb8aa3b, v169
	v_exp_f32_e32 v151, v151
	s_nop 0
	v_add_f32_e32 v151, 1.0, v151
	v_rcp_f32_e32 v171, v151
	s_nop 0
	v_pk_mul_f32 v[168:169], v[168:169], v[170:171]
	s_nop 0
	v_cvt_pk_bf16_f32 v165, v168, v169
	global_store_dwordx4 v[160:161], v[162:165], off offset:256
	s_nop 1
	v_mov_b32_e32 v166, v206
	v_lshl_add_u64 v[160:161], v[132:133], 0, s[0:1]
	s_mov_b32 s0, 0x50000
	v_pk_mul_f32 v[164:165], v[32:33], v[166:167] op_sel_hi:[1,0]
	s_nop 0
	v_mul_f32_e32 v151, 0xbfb8aa3b, v164
	v_exp_f32_e32 v151, v151
	v_pk_mul_f32 v[162:163], v[34:35], v[166:167] op_sel_hi:[1,0]
	v_pk_mul_f32 v[170:171], v[28:29], v[166:167] op_sel_hi:[1,0]
	v_add_f32_e32 v151, 1.0, v151
	v_rcp_f32_e32 v168, v151
	v_mul_f32_e32 v151, 0xbfb8aa3b, v165
	v_exp_f32_e32 v151, v151
	s_nop 0
	v_add_f32_e32 v151, 1.0, v151
	v_rcp_f32_e32 v169, v151
	v_mul_f32_e32 v151, 0xbfb8aa3b, v162
	v_exp_f32_e32 v151, v151
	v_pk_mul_f32 v[164:165], v[164:165], v[168:169]
	v_add_f32_e32 v151, 1.0, v151
	v_rcp_f32_e32 v168, v151
	v_mul_f32_e32 v151, 0xbfb8aa3b, v163
	v_exp_f32_e32 v151, v151
	s_nop 0
	v_add_f32_e32 v151, 1.0, v151
	v_rcp_f32_e32 v169, v151
	v_mul_f32_e32 v151, 0xbfb8aa3b, v170
	v_exp_f32_e32 v151, v151
	v_pk_mul_f32 v[168:169], v[162:163], v[168:169]
	v_pk_mul_f32 v[162:163], v[30:31], v[166:167] op_sel_hi:[1,0]
	v_add_f32_e32 v151, 1.0, v151
	v_rcp_f32_e32 v172, v151
	v_mul_f32_e32 v151, 0xbfb8aa3b, v171
	v_exp_f32_e32 v151, v151
	s_nop 0
	v_add_f32_e32 v151, 1.0, v151
	v_rcp_f32_e32 v173, v151
	v_mul_f32_e32 v151, 0xbfb8aa3b, v162
	v_exp_f32_e32 v151, v151
	v_pk_mul_f32 v[170:171], v[170:171], v[172:173]
	v_add_f32_e32 v151, 1.0, v151
	v_rcp_f32_e32 v172, v151
	v_mul_f32_e32 v151, 0xbfb8aa3b, v163
	v_exp_f32_e32 v151, v151
	s_nop 0
	v_add_f32_e32 v151, 1.0, v151
	v_rcp_f32_e32 v173, v151
	s_nop 0
	v_pk_mul_f32 v[172:173], v[162:163], v[172:173]
	v_cvt_pk_bf16_f32 v163, v168, v169
	v_add_co_u32_e32 v168, vcc, s0, v132
	v_cvt_pk_bf16_f32 v162, v164, v165
	v_cvt_pk_bf16_f32 v164, v170, v171
	v_cvt_pk_bf16_f32 v165, v172, v173
	v_addc_co_u32_e32 v169, vcc, 0, v133, vcc
	global_store_dwordx4 v[168:169], v[162:165], off
	s_mov_b64 s[0:1], 0x58000
	s_nop 0
	v_pk_mul_f32 v[162:163], v[24:25], v[166:167] op_sel_hi:[1,0]
	v_pk_mul_f32 v[164:165], v[26:27], v[166:167] op_sel_hi:[1,0]
	v_mul_f32_e32 v151, 0xbfb8aa3b, v162
	v_exp_f32_e32 v151, v151
	s_nop 0
	v_add_f32_e32 v151, 1.0, v151
	v_rcp_f32_e32 v168, v151
	v_mul_f32_e32 v151, 0xbfb8aa3b, v163
	v_exp_f32_e32 v151, v151
	s_nop 0
	v_add_f32_e32 v151, 1.0, v151
	v_rcp_f32_e32 v169, v151
	v_mul_f32_e32 v151, 0xbfb8aa3b, v164
	v_exp_f32_e32 v151, v151
	v_pk_mul_f32 v[162:163], v[162:163], v[168:169]
	s_nop 0
	v_cvt_pk_bf16_f32 v162, v162, v163
	v_add_f32_e32 v151, 1.0, v151
	v_rcp_f32_e32 v168, v151
	v_mul_f32_e32 v151, 0xbfb8aa3b, v165
	v_exp_f32_e32 v151, v151
	s_nop 0
	v_add_f32_e32 v151, 1.0, v151
	v_rcp_f32_e32 v169, v151
	s_nop 0
	v_pk_mul_f32 v[164:165], v[164:165], v[168:169]
	v_pk_mul_f32 v[168:169], v[22:23], v[166:167] op_sel_hi:[1,0]
	v_pk_mul_f32 v[166:167], v[20:21], v[166:167] op_sel_hi:[1,0]
	v_cvt_pk_bf16_f32 v163, v164, v165
	v_mul_f32_e32 v151, 0xbfb8aa3b, v166
	v_exp_f32_e32 v151, v151
	s_nop 0
	v_add_f32_e32 v151, 1.0, v151
	v_rcp_f32_e32 v170, v151
	v_mul_f32_e32 v151, 0xbfb8aa3b, v167
	v_exp_f32_e32 v151, v151
	s_nop 0
	v_add_f32_e32 v151, 1.0, v151
	v_rcp_f32_e32 v171, v151
	v_mul_f32_e32 v151, 0xbfb8aa3b, v168
	v_exp_f32_e32 v151, v151
	v_pk_mul_f32 v[166:167], v[166:167], v[170:171]
	s_nop 0
	v_cvt_pk_bf16_f32 v164, v166, v167
	v_add_f32_e32 v151, 1.0, v151
	v_rcp_f32_e32 v170, v151
	v_mul_f32_e32 v151, 0xbfb8aa3b, v169
	v_exp_f32_e32 v151, v151
	s_nop 0
	v_add_f32_e32 v151, 1.0, v151
	v_rcp_f32_e32 v171, v151
	s_nop 0
	v_pk_mul_f32 v[168:169], v[168:169], v[170:171]
	s_nop 0
	v_cvt_pk_bf16_f32 v165, v168, v169
	global_store_dwordx4 v[160:161], v[162:165], off offset:256
	s_nop 1
	v_mov_b32_e32 v164, v207
	v_lshl_add_u64 v[134:135], v[132:133], 0, s[0:1]
	s_mov_b32 s0, 0x58000
	v_add_co_u32_e32 v132, vcc, s0, v132
	s_nop 1
	v_addc_co_u32_e32 v133, vcc, 0, v133, vcc
	v_pk_mul_f32 v[162:163], v[16:17], v[164:165] op_sel_hi:[1,0]
	s_nop 0
	v_mul_f32_e32 v151, 0xbfb8aa3b, v162
	v_exp_f32_e32 v151, v151
	v_pk_mul_f32 v[160:161], v[18:19], v[164:165] op_sel_hi:[1,0]
	v_pk_mul_f32 v[168:169], v[12:13], v[164:165] op_sel_hi:[1,0]
	v_add_f32_e32 v151, 1.0, v151
	v_rcp_f32_e32 v166, v151
	v_mul_f32_e32 v151, 0xbfb8aa3b, v163
	v_exp_f32_e32 v151, v151
	s_nop 0
	v_add_f32_e32 v151, 1.0, v151
	v_rcp_f32_e32 v167, v151
	v_mul_f32_e32 v151, 0xbfb8aa3b, v160
	v_exp_f32_e32 v151, v151
	v_pk_mul_f32 v[162:163], v[162:163], v[166:167]
	v_add_f32_e32 v151, 1.0, v151
	v_rcp_f32_e32 v166, v151
	v_mul_f32_e32 v151, 0xbfb8aa3b, v161
	v_exp_f32_e32 v151, v151
	s_nop 0
	v_add_f32_e32 v151, 1.0, v151
	v_rcp_f32_e32 v167, v151
	v_mul_f32_e32 v151, 0xbfb8aa3b, v168
	v_exp_f32_e32 v151, v151
	v_pk_mul_f32 v[166:167], v[160:161], v[166:167]
	v_pk_mul_f32 v[160:161], v[14:15], v[164:165] op_sel_hi:[1,0]
	v_add_f32_e32 v151, 1.0, v151
	v_rcp_f32_e32 v170, v151
	v_mul_f32_e32 v151, 0xbfb8aa3b, v169
	v_exp_f32_e32 v151, v151
	s_nop 0
	v_add_f32_e32 v151, 1.0, v151
	v_rcp_f32_e32 v171, v151
	v_mul_f32_e32 v151, 0xbfb8aa3b, v160
	v_exp_f32_e32 v151, v151
	v_pk_mul_f32 v[168:169], v[168:169], v[170:171]
	v_add_f32_e32 v151, 1.0, v151
	v_rcp_f32_e32 v170, v151
	v_mul_f32_e32 v151, 0xbfb8aa3b, v161
	v_exp_f32_e32 v151, v151
	s_nop 0
	v_add_f32_e32 v151, 1.0, v151
	v_rcp_f32_e32 v171, v151
	s_nop 0
	v_pk_mul_f32 v[170:171], v[160:161], v[170:171]
	v_cvt_pk_bf16_f32 v160, v162, v163
	v_cvt_pk_bf16_f32 v161, v166, v167
	v_cvt_pk_bf16_f32 v162, v168, v169
	v_cvt_pk_bf16_f32 v163, v170, v171
	global_store_dwordx4 v[132:133], v[160:163], off
	v_pk_mul_f32 v[132:133], v[8:9], v[164:165] op_sel_hi:[1,0]
	s_nop 0
	v_mul_f32_e32 v151, 0xbfb8aa3b, v132
	v_exp_f32_e32 v151, v151
	v_pk_mul_f32 v[160:161], v[10:11], v[164:165] op_sel_hi:[1,0]
	v_add_f32_e32 v151, 1.0, v151
	v_rcp_f32_e32 v162, v151
	v_mul_f32_e32 v151, 0xbfb8aa3b, v133
	v_exp_f32_e32 v151, v151
	s_nop 0
	v_add_f32_e32 v151, 1.0, v151
	v_rcp_f32_e32 v163, v151
	v_mul_f32_e32 v151, 0xbfb8aa3b, v160
	v_exp_f32_e32 v151, v151
	v_pk_mul_f32 v[132:133], v[132:133], v[162:163]
	v_add_f32_e32 v151, 1.0, v151
	v_rcp_f32_e32 v162, v151
	v_mul_f32_e32 v151, 0xbfb8aa3b, v161
	v_exp_f32_e32 v151, v151
	s_nop 0
	v_add_f32_e32 v151, 1.0, v151
	v_rcp_f32_e32 v163, v151
	s_nop 0
	v_pk_mul_f32 v[160:161], v[160:161], v[162:163]
	v_pk_mul_f32 v[162:163], v[6:7], v[164:165] op_sel_hi:[1,0]
	v_pk_mul_f32 v[164:165], v[4:5], v[164:165] op_sel_hi:[1,0]
	s_nop 0
	v_mul_f32_e32 v151, 0xbfb8aa3b, v164
	v_exp_f32_e32 v151, v151
	s_nop 0
	v_add_f32_e32 v151, 1.0, v151
	v_rcp_f32_e32 v166, v151
	v_mul_f32_e32 v151, 0xbfb8aa3b, v165
	v_exp_f32_e32 v151, v151
	s_nop 0
	v_add_f32_e32 v151, 1.0, v151
	v_rcp_f32_e32 v167, v151
	v_mul_f32_e32 v151, 0xbfb8aa3b, v162
	v_exp_f32_e32 v151, v151
	v_pk_mul_f32 v[164:165], v[164:165], v[166:167]
	s_nop 0
	v_cvt_pk_bf16_f32 v164, v164, v165
	v_add_f32_e32 v151, 1.0, v151
	v_rcp_f32_e32 v166, v151
	v_mul_f32_e32 v151, 0xbfb8aa3b, v163
	v_exp_f32_e32 v151, v151
	s_nop 0
	v_add_f32_e32 v151, 1.0, v151
	v_rcp_f32_e32 v167, v151
	s_nop 0
	v_pk_mul_f32 v[166:167], v[162:163], v[166:167]
	v_cvt_pk_bf16_f32 v162, v132, v133
	v_cvt_pk_bf16_f32 v163, v160, v161
	v_cvt_pk_bf16_f32 v165, v166, v167
	global_store_dwordx4 v[134:135], v[162:165], off offset:256
	s_cbranch_execnz .LBB0_161

.LBB0_319:
	s_lshl_b32 s76, s94, 1
	s_and_b32 s0, s73, 15
	s_and_b32 s3, s74, 15
	s_sub_i32 s1, 14, s76
	s_lshl_b32 s2, s0, 21
	s_lshl_b32 s0, s3, 14
	s_lshl_b32 s46, s75, s1
	s_add_i32 s0, s46, s0
	s_lshl_b64 s[40:41], s[94:95], 25
	s_ashr_i32 s1, s0, 31
	s_lshl_b32 s42, s94, 26
	v_readlane_b32 s43, v255, 50
	s_add_u32 s42, s43, s42
	v_readlane_b32 s43, v255, 56
	s_addc_u32 s43, s43, 0
	s_lshl_b64 s[0:1], s[0:1], 7
	s_add_u32 s42, s42, s0
	s_addc_u32 s43, s43, s1
	s_max_u32 s44, s48, 1
	v_lshl_add_u32 v0, s44, 7, v86
	v_mov_b32_e32 v73, v2
	v_ashrrev_i32_e32 v1, 31, v0
	v_lshl_add_u64 v[20:21], s[42:43], 0, v[72:73]
	v_lshlrev_b64 v[0:1], 7, v[0:1]
	v_lshl_add_u64 v[0:1], v[20:21], 0, v[0:1]
	v_add_co_u32_e32 v8, vcc, s78, v0
	s_movk_i32 s47, 0x2000
	s_nop 0
	v_addc_co_u32_e32 v9, vcc, 0, v1, vcc
	v_add_co_u32_e32 v12, vcc, s47, v0
	global_load_dwordx4 v[156:159], v[0:1], off
	s_nop 0
	v_addc_co_u32_e32 v13, vcc, 0, v1, vcc
	s_mov_b32 s49, 0x2002000
	global_load_dwordx4 v[160:163], v[8:9], off
	v_add_co_u32_e32 v0, vcc, s49, v0
	global_load_dwordx4 v[164:167], v[12:13], off
	s_nop 0
	v_addc_co_u32_e32 v1, vcc, 0, v1, vcc
	global_load_dwordx4 v[168:171], v[0:1], off
	v_readlane_b32 s42, v255, 47
	s_add_u32 s44, s42, s40
	v_readlane_b32 s42, v255, 49
	s_addc_u32 s45, s42, s41
	s_lshl_b32 s90, s48, 7
	s_andn2_b32 s42, 0x80, s90
	v_add_u32_e32 v0, s42, v65
	v_mad_u64_u32 v[0:1], s[42:43], v0, s33, v[64:65]
	v_mov_b32_e32 v172, v0
	s_barrier
	v_add_u32_e32 v76, s90, v87
	s_add_u32 s0, s44, s0
	v_ashrrev_i32_e32 v77, 31, v76
	s_addc_u32 s1, s45, s1
	v_mov_b32_e32 v75, v2
	s_add_i32 s91, s48, 8
	v_readlane_b32 s42, v255, 52
	s_mov_b32 s77, 0
	v_add_u32_e32 v0, s90, v65
	v_ashrrev_i32_e32 v1, 31, v0
	v_lshlrev_b64 v[0:1], 7, v[0:1]
	v_lshl_add_u64 v[16:17], v[20:21], 0, v[0:1]
	v_add_co_u32_e32 v8, vcc, s78, v16
	v_lshlrev_b64 v[20:21], 7, v[76:77]
	s_nop 0
	v_addc_co_u32_e32 v9, vcc, 0, v17, vcc
	v_add_co_u32_e32 v12, vcc, s47, v16
	global_load_dwordx4 v[4:7], v[16:17], off
	s_nop 0
	v_addc_co_u32_e32 v13, vcc, 0, v17, vcc
	v_add_co_u32_e32 v16, vcc, s49, v16
	v_lshl_add_u64 v[22:23], s[0:1], 0, v[20:21]
	s_nop 0
	v_addc_co_u32_e32 v17, vcc, 0, v17, vcc
	v_lshl_add_u64 v[22:23], v[22:23], 0, v[74:75]
	global_load_dwordx4 v[8:11], v[8:9], off
	s_lshl_b64 s[0:1], s[94:95], 20
	global_load_dwordx4 v[12:15], v[12:13], off
	s_add_u32 s0, s42, s0
	global_load_dwordx4 v[16:19], v[16:17], off
	s_nop 0
	global_load_dwordx4 v[36:39], v[22:23], off
	global_load_dwordx4 v[32:35], v[22:23], off offset:64
	s_waitcnt vmcnt(9)
	ds_write_b128 v172, v[156:159]
	s_waitcnt vmcnt(8)
	ds_write_b128 v172, v[160:163] offset:36864
	s_waitcnt vmcnt(7)
	ds_write_b128 v172, v[164:167] offset:9216
	s_waitcnt vmcnt(6)
	ds_write_b128 v172, v[168:171] offset:46080
	v_readlane_b32 s42, v255, 54
	s_addc_u32 s1, s42, s1
	s_lshl_b32 s3, s3, 2
	s_add_u32 s0, s0, s3
	s_addc_u32 s1, s1, 0
	s_or_b32 s40, s40, s2
	v_add_u32_e32 v22, s90, v109
	v_lshl_add_u64 v[20:21], s[40:41], 0, v[20:21]
	s_lshl_b64 s[40:41], s[94:95], 26
	v_ashrrev_i32_e32 v23, 31, v22
	s_or_b32 s40, s40, s2
	v_lshlrev_b64 v[22:23], 7, v[22:23]
	v_lshl_add_u64 v[22:23], s[40:41], 0, v[22:23]
	s_ashr_i32 s47, s46, 31
	v_lshl_add_u64 v[78:79], v[66:67], 0, v[20:21]
	v_lshl_add_u64 v[80:81], v[68:69], 0, v[22:23]
	v_lshl_add_u64 v[0:1], s[40:41], 0, v[0:1]
	v_readlane_b32 s2, v255, 62
	v_lshl_add_u64 v[84:85], v[70:71], 0, v[20:21]
	s_lshl_b64 s[46:47], s[46:47], 7
	v_lshl_add_u64 v[82:83], v[68:69], 0, v[0:1]
	s_add_i32 s92, s2, s90
	s_add_i32 s93, s55, s90
	s_add_i32 s94, s56, s90
	s_add_i32 s96, s57, s90
	s_add_i32 s97, s58, s90
	s_add_i32 s98, s59, s90
	s_add_i32 s99, s60, s90
	s_add_i32 s44, s61, s90
	s_add_i32 s45, s62, s90
	s_add_i32 s42, s63, s90
	s_add_i32 s3, s64, s90
	s_add_i32 s78, s65, s90
	s_add_i32 s79, s66, s90
	s_add_i32 s2, s67, s90
	s_add_i32 s43, s68, s90
	s_add_i32 s50, s69, s90
	s_add_i32 s51, s70, s90
	s_add_i32 s52, s71, s90
	s_add_i32 s53, s72, s90
	s_add_i32 s54, s48, 1
	s_waitcnt vmcnt(1)
	v_mov_b64_e32 v[24:25], v[36:37]
	s_waitcnt vmcnt(0)
	v_mov_b64_e32 v[20:21], v[32:33]
	v_mov_b64_e32 v[22:23], v[34:35]
	v_mov_b64_e32 v[26:27], v[38:39]
	s_branch .LBB0_321
